# w_out tail consumer: L1 invalidate issued before the flag poll instead of after
# speedup vs baseline: 1.0043x; 1.0043x over previous
; __device__ __forceinline__ int lane_id_v() { int l; asm volatile("v_mbcnt_lo_u32_b32 %0, -1, 0\n\tv_mbcnt_hi_u32_b32 %0, -1, %0" : "=v"(l)); return l; }
; __device__ __forceinline__ void st_bf4(bf16_t* p, const f32x4 v) { u32x2 w; w.x = cvt_pk_bf16(v[0], v[1]); w.y = cvt_pk_bf16(v[2], v[3]); *(u32x2*)p = w; }
; __global__ void __launch_bounds__(512, 2) mega(Args a_unused) {
;     ...
;                 for (int j = c; j < 64; j += G) { const int ks = j & 7, pmr = j >> 5; const float* Pm = (const float*)(ws + WS_Q);
;                     for (int e2 = wave_s * 64 + lane_id_v(); e2 < 256 * 32; e2 += 512) { const int rs = pmr * 256 + (e2 >> 5), c4 = ks * 128 + (e2 & 31) * 4; f32x4 s = {0.f, 0.f, 0.f, 0.f};
; #pragma unroll
;                         for (int p = 0; p < 12; ++p) s += *(const f32x4*)(Pm + ((size_t)p * 512 + rs) * 1024 + c4);
;                         st_bf4(H + (size_t)(MP + rs) * 1024 + c4, s); } }
;                 asm volatile("s_waitcnt vmcnt(0)" ::: "memory"); __syncthreads();
.LBB0_256:
	s_cmp_lt_i32 s38, 64
	s_cselect_b64 s[2:3], -1, 0
	s_cmp_gt_i32 s38, 63
	s_cbranch_scc1 .LBB0_262
	s_cmpk_lg_i32 s51, 0x100
	s_cbranch_scc1 .Lwc_orig
	v_cmp_eq_u32_e64 s[6:7], 0, v194
	s_and_saveexec_b64 s[8:9], s[6:7]
	s_cbranch_execz .Lwc_done
	v_mov_b32_e32 v2, 0x3c00
	v_mov_b32_e32 v3, 0
	v_lshl_add_u64 v[2:3], s[26:27], 0, v[2:3]
	buffer_inv sc1
.Lwc_poll:
	flat_load_dword v0, v[2:3] sc1
	s_waitcnt vmcnt(0) lgkmcnt(0)
	v_cmp_le_u32_e64 s[10:11], s100, v0
	s_and_b64 vcc, exec, s[10:11]
	s_cbranch_vccnz .Lwc_done
	s_sleep 2
	s_branch .Lwc_poll
.Lwc_done:
	s_or_b64 exec, exec, s[8:9]
	s_branch .LBB0_262
